# conv_gu loads without the nt hint (second read of a matrix the column-maximum pass just read) and in descending k order
# baseline (speedup 1.0000x reference)
.LBB0_65:
	s_mul_hi_i32 s46, s45, 0x2fa0be83
	s_lshr_b32 s47, s46, 31
	s_ashr_i32 s46, s46, 6
	s_add_i32 s84, s46, s47
	s_mul_i32 s46, s84, 0xffffd500
	s_mul_i32 s47, s84, 0xffffaa00
	s_add_i32 s46, s43, s46
	s_add_i32 s47, s44, s47
	s_and_b32 s48, s46, 0x60
	s_and_b32 s47, s47, 0xffffff00
	s_or_b32 s48, s48, s40
	s_mul_i32 s80, s84, 0x2b0000
	s_or_b32 s48, s48, s47
	s_mul_hi_i32 s49, s84, 0x2b0000
	s_add_u32 s80, s42, s80
	s_addc_u32 s49, s41, s49
	s_ashr_i32 s47, s46, 31
	s_lshl_b64 s[46:47], s[46:47], 2
	s_add_u32 s46, s80, s46
	s_addc_u32 s47, s49, s47
	v_mov_b32_e32 v13, v143
	v_mov_b32_e32 v15, v143
	v_mov_b32_e32 v17, v143
	v_mov_b32_e32 v19, v143
	v_mov_b32_e32 v21, v143
	v_lshl_add_u64 v[2:3], s[46:47], 0, v[142:143]
	v_lshl_add_u64 v[48:49], v[2:3], 0, v[12:13]
	v_lshl_add_u64 v[26:27], v[2:3], 0, v[14:15]
	v_lshl_add_u64 v[36:37], v[2:3], 0, v[16:17]
	v_lshl_add_u64 v[40:41], v[2:3], 0, v[18:19]
	v_lshl_add_u64 v[2:3], v[2:3], 0, v[20:21]
	global_load_dwordx4 v[22:25], v[48:49], off
	s_nop 0
	global_load_dwordx4 v[26:29], v[26:27], off
	s_nop 0
	global_load_dwordx4 v[36:39], v[36:37], off
	s_nop 0
	global_load_dwordx4 v[40:43], v[40:41], off
	s_nop 0
	global_load_dwordx4 v[44:47], v[2:3], off
	v_add_co_u32_e32 v2, vcc, s53, v48
	v_add_u32_e32 v35, v30, v31
	s_nop 0
	v_addc_co_u32_e32 v3, vcc, 0, v49, vcc
	v_add_co_u32_e32 v52, vcc, s79, v48
	v_add_u32_e32 v62, 0x420, v35
	s_nop 0
	v_addc_co_u32_e32 v53, vcc, 0, v49, vcc
	v_add_co_u32_e32 v56, vcc, s33, v48
	v_add_u32_e32 v63, 0x428, v35
	s_nop 0
	v_addc_co_u32_e32 v57, vcc, 0, v49, vcc
	global_load_dwordx4 v[48:51], v[2:3], off
	s_nop 0
	global_load_dwordx4 v[52:55], v[52:53], off
	s_nop 0
	global_load_dwordx4 v[56:59], v[56:57], off
	v_add_u32_e32 v65, 0x840, v35
	v_add_u32_e32 v66, 0x848, v35
	v_add_u32_e32 v67, 0xc60, v35
	v_add_u32_e32 v68, 0xc68, v35
	v_add_u32_e32 v69, 0x1080, v35
	v_add_u32_e32 v70, 0x1088, v35
	v_add_u32_e32 v71, 0x14a0, v35
	v_add_u32_e32 v72, 0x14a8, v35
	v_add_u32_e32 v73, 0x18c0, v35
	v_add_u32_e32 v74, 0x18c8, v35
	v_add_u32_e32 v75, 0x1ce0, v35
	v_add_u32_e32 v76, 0x1ce8, v35
	s_ashr_i32 s49, s48, 31
	v_lshl_add_u64 v[4:5], s[48:49], 2, v[10:11]
	s_lshl_b64 s[80:81], s[48:49], 12
	s_add_u32 s46, s51, s80
	s_addc_u32 s47, s52, s81
	s_lshl_b32 s48, s84, 6
	s_ashr_i32 s49, s48, 31
	s_add_u32 s46, s46, s48
	s_addc_u32 s47, s47, s49
	v_lshl_add_u64 v[2:3], s[46:47], 0, v[144:145]
	v_add_u32_e32 v64, 0x400, v149
	v_lshl_add_u64 v[60:61], v[2:3], 0, v[6:7]
	s_sub_i32 s45, s45, s8
	s_sub_i32 s43, s43, s37
	s_sub_i32 s44, s44, s55
	s_cmp_gt_i32 s45, -1
	s_waitcnt vmcnt(7)
	ds_write2_b32 v35, v22, v23 offset1:1
	ds_write2_b32 v35, v24, v25 offset0:2 offset1:3
	s_waitcnt vmcnt(6)
	ds_write2_b32 v69, v26, v27 offset1:1
	ds_write2_b32 v70, v28, v29 offset1:1
	s_waitcnt vmcnt(5)
	ds_write2_b32 v71, v36, v37 offset1:1
	ds_write2_b32 v72, v38, v39 offset1:1
	s_waitcnt vmcnt(4)
	ds_write2_b32 v73, v40, v41 offset1:1
	ds_write2_b32 v74, v42, v43 offset1:1
	s_waitcnt vmcnt(3)
	ds_write2_b32 v75, v44, v45 offset1:1
	ds_write2_b32 v76, v46, v47 offset1:1
	s_waitcnt vmcnt(2)
	ds_write2_b32 v62, v48, v49 offset1:1
	ds_write2_b32 v63, v50, v51 offset1:1
	s_waitcnt vmcnt(1)
	ds_write2_b32 v65, v52, v53 offset1:1
	ds_write2_b32 v66, v54, v55 offset1:1
	s_waitcnt vmcnt(0)
	ds_write2_b32 v67, v56, v57 offset1:1
	ds_write2_b32 v68, v58, v59 offset1:1
	s_waitcnt lgkmcnt(0)
	global_load_dword v13, v[4:5], off
	ds_read2_b32 v[26:27], v149 offset1:16
	ds_read2_b32 v[28:29], v149 offset0:33 offset1:49
	ds_read2_b32 v[36:37], v149 offset0:66 offset1:82
	ds_read2_b32 v[38:39], v149 offset0:99 offset1:115
	ds_read2_b32 v[40:41], v149 offset0:132 offset1:148
	ds_read2_b32 v[42:43], v149 offset0:165 offset1:181
	ds_read2_b32 v[44:45], v149 offset0:198 offset1:214
	ds_read2_b32 v[46:47], v149 offset0:231 offset1:247
	ds_read2_b32 v[48:49], v64 offset0:8 offset1:24
	ds_read2_b32 v[50:51], v64 offset0:41 offset1:57
	ds_read2_b32 v[52:53], v64 offset0:74 offset1:90
	ds_read2_b32 v[54:55], v64 offset0:107 offset1:123
	ds_read2_b32 v[56:57], v64 offset0:140 offset1:156
	ds_read2_b32 v[58:59], v64 offset0:173 offset1:189
	ds_read2_b32 v[62:63], v64 offset0:206 offset1:222
	ds_read2_b32 v[64:65], v64 offset0:239 offset1:255
	s_waitcnt lgkmcnt(14)
	v_mov_b32_e32 v22, v26
	v_mov_b32_e32 v24, v28
	s_waitcnt lgkmcnt(10)
	v_mov_b32_e32 v25, v42
	v_mov_b32_e32 v68, v38
	s_waitcnt lgkmcnt(8)
	v_mov_b32_e32 v69, v46
	s_waitcnt lgkmcnt(6)
	v_mov_b32_e32 v72, v50
	s_waitcnt lgkmcnt(2)
	v_mov_b32_e32 v73, v58
	v_mov_b32_e32 v74, v52
	s_waitcnt lgkmcnt(1)
	v_mov_b32_e32 v75, v62
	v_mov_b32_e32 v76, v54
	s_waitcnt lgkmcnt(0)
	v_mov_b32_e32 v77, v64
	v_mov_b32_e32 v23, v40
	v_mov_b32_e32 v66, v36
	v_mov_b32_e32 v67, v44
	v_mov_b32_e32 v70, v48
	v_mov_b32_e32 v71, v56
	v_mov_b32_e32 v40, v27
	v_mov_b32_e32 v42, v29
	v_mov_b32_e32 v44, v37
	v_mov_b32_e32 v46, v39
	v_mov_b32_e32 v56, v49
	v_mov_b32_e32 v58, v51
	v_mov_b32_e32 v62, v53
	v_mov_b32_e32 v64, v55
	s_waitcnt vmcnt(0)
	v_div_scale_f32 v15, s[46:47], v13, v13, s90
	v_rcp_f32_e32 v19, v15
	v_div_scale_f32 v17, vcc, s90, v13, s90
	v_fma_f32 v21, -v15, v19, 1.0
	v_fmac_f32_e32 v19, v21, v19
	v_mul_f32_e32 v21, v17, v19
	v_fma_f32 v26, -v15, v21, v17
	v_fmac_f32_e32 v21, v26, v19
	v_fma_f32 v15, -v15, v21, v17
	v_div_fmas_f32 v15, v15, v19, v21
	v_div_fixup_f32 v15, v15, v13, s90
	v_cmp_lt_f32_e32 vcc, 0, v13
	s_nop 1
	v_cndmask_b32_e32 v26, 0, v15, vcc
	v_pk_fma_f32 v[24:25], v[24:25], v[26:27], s[78:79] op_sel_hi:[1,0,0]
	v_pk_fma_f32 v[68:69], v[68:69], v[26:27], s[78:79] op_sel_hi:[1,0,0]
	v_pk_fma_f32 v[72:73], v[72:73], v[26:27], s[78:79] op_sel_hi:[1,0,0]
	v_pk_fma_f32 v[74:75], v[74:75], v[26:27], s[78:79] op_sel_hi:[1,0,0]
	v_pk_fma_f32 v[76:77], v[76:77], v[26:27], s[78:79] op_sel_hi:[1,0,0]
	v_pk_fma_f32 v[22:23], v[22:23], v[26:27], s[78:79] op_sel_hi:[1,0,0]
	v_pk_fma_f32 v[66:67], v[66:67], v[26:27], s[78:79] op_sel_hi:[1,0,0]
	v_pk_fma_f32 v[70:71], v[70:71], v[26:27], s[78:79] op_sel_hi:[1,0,0]
	v_lshlrev_b32_e32 v13, 8, v25
	v_lshlrev_b32_e32 v15, 8, v24
	v_lshlrev_b32_e32 v21, 24, v69
	v_lshlrev_b32_e32 v24, 24, v68
	v_lshlrev_b32_e32 v25, 8, v73
	v_lshlrev_b32_e32 v26, 8, v72
	v_lshlrev_b32_e32 v28, 16, v75
	v_lshlrev_b32_e32 v35, 16, v74
	v_lshlrev_b32_e32 v36, 24, v77
	v_lshlrev_b32_e32 v38, 24, v76
	v_lshlrev_b32_e32 v17, 16, v67
	v_lshlrev_b32_e32 v19, 16, v66
	v_and_b32_e32 v13, 0xff00, v13
	v_and_b32_e32 v15, 0xff00, v15
	v_or_b32_sdwa v21, v21, v23 dst_sel:DWORD dst_unused:UNUSED_PAD src0_sel:DWORD src1_sel:BYTE_0
	v_or_b32_sdwa v22, v24, v22 dst_sel:DWORD dst_unused:UNUSED_PAD src0_sel:DWORD src1_sel:BYTE_0
	v_and_b32_e32 v23, 0xff00, v25
	v_and_b32_e32 v24, 0xff00, v26
	v_and_b32_e32 v25, 0xff0000, v28
	v_and_b32_e32 v26, 0xff0000, v35
	v_or_b32_sdwa v28, v36, v71 dst_sel:DWORD dst_unused:UNUSED_PAD src0_sel:DWORD src1_sel:BYTE_0
	v_or_b32_sdwa v35, v38, v70 dst_sel:DWORD dst_unused:UNUSED_PAD src0_sel:DWORD src1_sel:BYTE_0
	v_and_b32_e32 v17, 0xff0000, v17
	v_and_b32_e32 v19, 0xff0000, v19
	v_or_b32_e32 v13, v21, v13
	v_or_b32_e32 v15, v22, v15
	v_or_b32_e32 v21, v28, v23
	v_or_b32_e32 v24, v35, v24
	v_or_b32_e32 v23, v13, v17
	v_or_b32_e32 v22, v15, v19
	v_or_b32_e32 v25, v21, v25
	v_or_b32_e32 v24, v24, v26
	global_store_dwordx4 v[60:61], v[22:25], off
	global_load_dword v4, v[4:5], off offset:64
	s_nop 0
	v_lshl_add_u64 v[22:23], v[2:3], 0, v[146:147]
	s_waitcnt vmcnt(0)
	v_div_scale_f32 v2, s[46:47], v4, v4, s90
	v_rcp_f32_e32 v5, v2
	v_div_scale_f32 v3, vcc, s90, v4, s90
	v_fma_f32 v13, -v2, v5, 1.0
	v_fmac_f32_e32 v5, v13, v5
	v_mul_f32_e32 v13, v3, v5
	v_fma_f32 v15, -v2, v13, v3
	v_fmac_f32_e32 v13, v15, v5
	v_fma_f32 v2, -v2, v13, v3
	v_div_fmas_f32 v2, v2, v5, v13
	v_div_fixup_f32 v2, v2, v4, s90
	v_cmp_lt_f32_e32 vcc, 0, v4
	s_nop 1
	v_cndmask_b32_e32 v2, 0, v2, vcc
	v_pk_fma_f32 v[4:5], v[40:41], v[2:3], s[78:79] op_sel_hi:[1,0,0]
	v_pk_fma_f32 v[24:25], v[42:43], v[2:3], s[78:79] op_sel_hi:[1,0,0]
	v_pk_fma_f32 v[26:27], v[44:45], v[2:3], s[78:79] op_sel_hi:[1,0,0]
	v_pk_fma_f32 v[28:29], v[46:47], v[2:3], s[78:79] op_sel_hi:[1,0,0]
	v_pk_fma_f32 v[36:37], v[56:57], v[2:3], s[78:79] op_sel_hi:[1,0,0]
	v_pk_fma_f32 v[38:39], v[58:59], v[2:3], s[78:79] op_sel_hi:[1,0,0]
	v_pk_fma_f32 v[40:41], v[62:63], v[2:3], s[78:79] op_sel_hi:[1,0,0]
	v_pk_fma_f32 v[2:3], v[64:65], v[2:3], s[78:79] op_sel_hi:[1,0,0]
	v_lshlrev_b32_e32 v13, 8, v25
	v_lshlrev_b32_e32 v15, 8, v24
	v_lshlrev_b32_e32 v19, 16, v26
	v_lshlrev_b32_e32 v21, 24, v29
	v_lshlrev_b32_e32 v24, 24, v28
	v_lshlrev_b32_e32 v25, 8, v39
	v_lshlrev_b32_e32 v26, 8, v38
	v_lshlrev_b32_e32 v3, 24, v3
	v_lshlrev_b32_e32 v2, 24, v2
	v_lshlrev_b32_e32 v17, 16, v27
	v_lshlrev_b32_e32 v27, 16, v41
	v_lshlrev_b32_e32 v28, 16, v40
	v_and_b32_e32 v13, 0xff00, v13
	v_and_b32_e32 v15, 0xff00, v15
	v_or_b32_sdwa v5, v21, v5 dst_sel:DWORD dst_unused:UNUSED_PAD src0_sel:DWORD src1_sel:BYTE_0
	v_or_b32_sdwa v4, v24, v4 dst_sel:DWORD dst_unused:UNUSED_PAD src0_sel:DWORD src1_sel:BYTE_0
	v_and_b32_e32 v21, 0xff00, v25
	v_and_b32_e32 v24, 0xff00, v26
	v_or_b32_sdwa v3, v3, v37 dst_sel:DWORD dst_unused:UNUSED_PAD src0_sel:DWORD src1_sel:BYTE_0
	v_or_b32_sdwa v2, v2, v36 dst_sel:DWORD dst_unused:UNUSED_PAD src0_sel:DWORD src1_sel:BYTE_0
	v_and_b32_e32 v17, 0xff0000, v17
	v_and_b32_e32 v19, 0xff0000, v19
	v_and_b32_e32 v25, 0xff0000, v27
	v_and_b32_e32 v26, 0xff0000, v28
	v_or_b32_e32 v5, v5, v13
	v_or_b32_e32 v4, v4, v15
	v_or_b32_e32 v13, v3, v21
	v_or_b32_e32 v15, v2, v24
	v_or_b32_e32 v3, v5, v17
	v_or_b32_e32 v2, v4, v19
	v_or_b32_e32 v5, v13, v25
	v_or_b32_e32 v4, v15, v26
	global_store_dwordx4 v[22:23], v[2:5], off
	s_waitcnt lgkmcnt(0)
	s_cbranch_scc1 .LBB0_65
	s_branch .LBB0_7
